# snake MFMA order + s_sleep 2 in the load segments of the FFN-in, QKV and conv-in GEMM loops
# baseline (speedup 1.0000x reference)
; template <class Epi, class Sched, bool ALIGN_EPI = false, bool SP2 = false>
; __device__ __forceinline__ void gemm_phase(PG8_LAS unsigned char* lds, const Gemm g, const Sched& S, const Epi& E) {
;     ...
;         if constexpr (Epi::PEEL) {
;             const char* a1 = cA + kstepA; const char* a2 = cA + 2 * kstepA; const char* b2 = cB + 2 * kstepB; const char* a3 = a2 + kstepA; const char* b3 = b2 + kstepB;
;             PG8_ITER(8);
;         }
;         for (int t = (Epi::PEEL ? 2 : 0); t < nt; t += 2) {
;             const bool last = (t == nt - 2);
;             const char* a1 = cA + (size_t)(t + 1) * kstepA;
;             const char* a2 = last ? nA : cA + (size_t)(t + 2) * kstepA; const char* b2 = last ? nB : cB + (size_t)(t + 2) * kstepB;
;             const char* a3 = a2 + kstepA; const char* b3 = b2 + kstepB;
;             PG8_ITER(8);
.LBB0_161:
	ds_read_b128 v[146:149], v142
	ds_read_b128 v[150:153], v142 offset:1024
	ds_read_b128 v[154:157], v142 offset:2048
	ds_read_b128 v[162:165], v142 offset:3072
	ds_read_b128 v[166:169], v143
	ds_read_b128 v[170:173], v143 offset:1024
	ds_read_b128 v[174:177], v143 offset:2048
	ds_read_b128 v[180:183], v143 offset:3072
	s_add_u32 s8, s0, 0x3fc000
	s_addc_u32 s9, s1, 0
	s_cmp_eq_u32 s18, 12
	s_cselect_b32 s28, s44, s8
	s_cselect_b32 s29, s27, s9
	s_cselect_b32 s42, s49, s3
	s_cselect_b32 s43, s45, s2
	s_add_u32 s24, s28, 0x400000
	s_addc_u32 s25, s29, 0
	s_mov_b32 m0, s50
	v_lshl_add_u64 v[158:159], s[0:1], 0, v[140:141]
	ds_read_b128 v[184:187], v161
	ds_read_b128 v[188:191], v161 offset:1024
	ds_read_b128 v[192:195], v161 offset:2048
	ds_read_b128 v[196:199], v161 offset:3072
	ds_read_b128 v[200:203], v161 offset:4096
	ds_read_b128 v[204:207], v161 offset:5120
	ds_read_b128 v[208:211], v161 offset:6144
	ds_read_b128 v[212:215], v161 offset:7168
	global_load_lds_dwordx4 v[158:159], off
	v_lshl_add_u64 v[158:159], s[0:1], 0, v[138:139]
	s_mov_b32 m0, s51
	s_nop 0
	global_load_lds_dwordx4 v[158:159], off
	s_sleep 2
	s_waitcnt vmcnt(8)
	s_waitcnt lgkmcnt(0)
	s_barrier
	s_setprio 1
	s_waitcnt lgkmcnt(0)
	v_mfma_f32_16x16x32_bf16 v[126:129], v[146:149], v[184:187], v[126:129]
	v_mfma_f32_16x16x32_bf16 v[118:121], v[154:157], v[184:187], v[118:121]
	v_mfma_f32_16x16x32_bf16 v[102:105], v[154:157], v[192:195], v[102:105]
	v_mfma_f32_16x16x32_bf16 v[110:113], v[146:149], v[192:195], v[110:113]
	v_mfma_f32_16x16x32_bf16 v[92:95], v[146:149], v[200:203], v[92:95]
	v_mfma_f32_16x16x32_bf16 v[84:87], v[154:157], v[200:203], v[84:87]
	v_mfma_f32_16x16x32_bf16 v[68:71], v[154:157], v[208:211], v[68:71]
	v_mfma_f32_16x16x32_bf16 v[76:79], v[146:149], v[208:211], v[76:79]
	v_mfma_f32_16x16x32_bf16 v[126:129], v[150:153], v[188:191], v[126:129]
	v_mfma_f32_16x16x32_bf16 v[118:121], v[162:165], v[188:191], v[118:121]
	v_mfma_f32_16x16x32_bf16 v[102:105], v[162:165], v[196:199], v[102:105]
	v_mfma_f32_16x16x32_bf16 v[110:113], v[150:153], v[196:199], v[110:113]
	v_mfma_f32_16x16x32_bf16 v[92:95], v[150:153], v[204:207], v[92:95]
	v_mfma_f32_16x16x32_bf16 v[84:87], v[162:165], v[204:207], v[84:87]
	v_mfma_f32_16x16x32_bf16 v[68:71], v[162:165], v[212:215], v[68:71]
	v_mfma_f32_16x16x32_bf16 v[76:79], v[150:153], v[212:215], v[76:79]
	s_setprio 0
	s_setprio 1
	v_mfma_f32_16x16x32_bf16 v[122:125], v[166:169], v[184:187], v[122:125]
	v_mfma_f32_16x16x32_bf16 v[114:117], v[174:177], v[184:187], v[114:117]
	v_mfma_f32_16x16x32_bf16 v[98:101], v[174:177], v[192:195], v[98:101]
	v_mfma_f32_16x16x32_bf16 v[106:109], v[166:169], v[192:195], v[106:109]
	v_mfma_f32_16x16x32_bf16 v[88:91], v[166:169], v[200:203], v[88:91]
	v_mfma_f32_16x16x32_bf16 v[80:83], v[174:177], v[200:203], v[80:83]
	v_mfma_f32_16x16x32_bf16 v[64:67], v[174:177], v[208:211], v[64:67]
	v_mfma_f32_16x16x32_bf16 v[72:75], v[166:169], v[208:211], v[72:75]
	v_mfma_f32_16x16x32_bf16 v[122:125], v[170:173], v[188:191], v[122:125]
	v_mfma_f32_16x16x32_bf16 v[114:117], v[180:183], v[188:191], v[114:117]
	v_mfma_f32_16x16x32_bf16 v[98:101], v[180:183], v[196:199], v[98:101]
	v_mfma_f32_16x16x32_bf16 v[106:109], v[170:173], v[196:199], v[106:109]
	v_mfma_f32_16x16x32_bf16 v[88:91], v[170:173], v[204:207], v[88:91]
	v_mfma_f32_16x16x32_bf16 v[80:83], v[180:183], v[204:207], v[80:83]
	v_mfma_f32_16x16x32_bf16 v[64:67], v[180:183], v[212:215], v[64:67]
	v_mfma_f32_16x16x32_bf16 v[72:75], v[170:173], v[212:215], v[72:75]
	s_setprio 0
	s_barrier
	s_mov_b32 m0, s55
	v_lshl_add_u64 v[158:159], s[42:43], 0, v[132:133]
	s_add_u32 s8, s42, 0x40000
	ds_read_b128 v[184:187], v161 offset:16384
	ds_read_b128 v[188:191], v161 offset:17408
	ds_read_b128 v[192:195], v161 offset:18432
	ds_read_b128 v[196:199], v161 offset:19456
	ds_read_b128 v[200:203], v161 offset:20480
	ds_read_b128 v[204:207], v161 offset:21504
	ds_read_b128 v[208:211], v161 offset:22528
	ds_read_b128 v[212:215], v161 offset:23552
	global_load_lds_dwordx4 v[158:159], off
	v_lshl_add_u64 v[178:179], s[42:43], 0, v[136:137]
	s_mov_b32 m0, vcc_lo
	s_addc_u32 s9, s43, 0
	global_load_lds_dwordx4 v[178:179], off
	v_lshl_add_u64 v[216:217], s[8:9], 0, v[132:133]
	s_mov_b32 m0, vcc_hi
	s_nop 0
	global_load_lds_dwordx4 v[216:217], off
	v_lshl_add_u64 v[216:217], s[8:9], 0, v[136:137]
	s_mov_b32 m0, s56
	s_nop 0
	global_load_lds_dwordx4 v[216:217], off
	v_lshl_add_u64 v[216:217], s[28:29], 0, v[130:131]
	s_mov_b32 m0, s22
	s_nop 0
	global_load_lds_dwordx4 v[216:217], off
	v_lshl_add_u64 v[216:217], s[28:29], 0, v[134:135]
	s_mov_b32 m0, s23
	s_nop 0
	global_load_lds_dwordx4 v[216:217], off
	s_sleep 2
	s_waitcnt vmcnt(8)
	s_waitcnt lgkmcnt(0)
	s_barrier
	s_setprio 1
	s_waitcnt lgkmcnt(0)
	v_mfma_f32_16x16x32_bf16 v[60:63], v[146:149], v[184:187], v[60:63]
	v_mfma_f32_16x16x32_bf16 v[52:55], v[154:157], v[184:187], v[52:55]
	v_mfma_f32_16x16x32_bf16 v[36:39], v[154:157], v[192:195], v[36:39]
	v_mfma_f32_16x16x32_bf16 v[44:47], v[146:149], v[192:195], v[44:47]
	v_mfma_f32_16x16x32_bf16 v[28:31], v[146:149], v[200:203], v[28:31]
	v_mfma_f32_16x16x32_bf16 v[20:23], v[154:157], v[200:203], v[20:23]
	v_mfma_f32_16x16x32_bf16 v[4:7], v[154:157], v[208:211], v[4:7]
	v_mfma_f32_16x16x32_bf16 v[12:15], v[146:149], v[208:211], v[12:15]
	v_mfma_f32_16x16x32_bf16 v[60:63], v[150:153], v[188:191], v[60:63]
	v_mfma_f32_16x16x32_bf16 v[52:55], v[162:165], v[188:191], v[52:55]
	v_mfma_f32_16x16x32_bf16 v[36:39], v[162:165], v[196:199], v[36:39]
	v_mfma_f32_16x16x32_bf16 v[44:47], v[150:153], v[196:199], v[44:47]
	v_mfma_f32_16x16x32_bf16 v[28:31], v[150:153], v[204:207], v[28:31]
	v_mfma_f32_16x16x32_bf16 v[20:23], v[162:165], v[204:207], v[20:23]
	v_mfma_f32_16x16x32_bf16 v[4:7], v[162:165], v[212:215], v[4:7]
	v_mfma_f32_16x16x32_bf16 v[12:15], v[150:153], v[212:215], v[12:15]
	s_setprio 0
	s_setprio 1
	v_mfma_f32_16x16x32_bf16 v[56:59], v[166:169], v[184:187], v[56:59]
	v_mfma_f32_16x16x32_bf16 v[48:51], v[174:177], v[184:187], v[48:51]
	v_mfma_f32_16x16x32_bf16 v[32:35], v[174:177], v[192:195], v[32:35]
	v_mfma_f32_16x16x32_bf16 v[40:43], v[166:169], v[192:195], v[40:43]
	v_mfma_f32_16x16x32_bf16 v[24:27], v[166:169], v[200:203], v[24:27]
	v_mfma_f32_16x16x32_bf16 v[16:19], v[174:177], v[200:203], v[16:19]
	v_mfma_f32_16x16x32_bf16 v[0:3], v[174:177], v[208:211], v[0:3]
	v_mfma_f32_16x16x32_bf16 v[8:11], v[166:169], v[208:211], v[8:11]
	v_mfma_f32_16x16x32_bf16 v[56:59], v[170:173], v[188:191], v[56:59]
	v_mfma_f32_16x16x32_bf16 v[48:51], v[180:183], v[188:191], v[48:51]
	v_mfma_f32_16x16x32_bf16 v[32:35], v[180:183], v[196:199], v[32:35]
	v_mfma_f32_16x16x32_bf16 v[40:43], v[170:173], v[196:199], v[40:43]
	v_mfma_f32_16x16x32_bf16 v[24:27], v[170:173], v[204:207], v[24:27]
	v_mfma_f32_16x16x32_bf16 v[16:19], v[180:183], v[204:207], v[16:19]
	v_mfma_f32_16x16x32_bf16 v[0:3], v[180:183], v[212:215], v[0:3]
	v_mfma_f32_16x16x32_bf16 v[8:11], v[170:173], v[212:215], v[8:11]
	s_setprio 0
	s_barrier
	ds_read_b128 v[146:149], v144
	ds_read_b128 v[150:153], v144 offset:1024
	ds_read_b128 v[154:157], v144 offset:2048
	ds_read_b128 v[162:165], v144 offset:3072
	ds_read_b128 v[166:169], v145
	ds_read_b128 v[170:173], v145 offset:1024
	ds_read_b128 v[174:177], v145 offset:2048
	ds_read_b128 v[180:183], v145 offset:3072
	s_add_u32 s8, s28, 0x4000
	s_addc_u32 s9, s29, 0
	s_mov_b32 m0, s39
	v_lshl_add_u64 v[216:217], s[8:9], 0, v[130:131]
	ds_read_b128 v[184:187], v161 offset:32768
	ds_read_b128 v[188:191], v161 offset:33792
	ds_read_b128 v[192:195], v161 offset:34816
	ds_read_b128 v[196:199], v161 offset:35840
	ds_read_b128 v[200:203], v161 offset:36864
	ds_read_b128 v[204:207], v161 offset:37888
	ds_read_b128 v[208:211], v161 offset:38912
	ds_read_b128 v[212:215], v161 offset:39936
	global_load_lds_dwordx4 v[216:217], off
	v_lshl_add_u64 v[216:217], s[8:9], 0, v[134:135]
	s_mov_b32 m0, s52
	s_nop 0
	global_load_lds_dwordx4 v[216:217], off
	s_sleep 2
	s_waitcnt vmcnt(8)
	s_waitcnt lgkmcnt(0)
	s_barrier
	s_setprio 1
	s_waitcnt lgkmcnt(0)
	v_mfma_f32_16x16x32_bf16 v[126:129], v[146:149], v[184:187], v[126:129]
	v_mfma_f32_16x16x32_bf16 v[118:121], v[154:157], v[184:187], v[118:121]
	v_mfma_f32_16x16x32_bf16 v[102:105], v[154:157], v[192:195], v[102:105]
	v_mfma_f32_16x16x32_bf16 v[110:113], v[146:149], v[192:195], v[110:113]
	v_mfma_f32_16x16x32_bf16 v[92:95], v[146:149], v[200:203], v[92:95]
	v_mfma_f32_16x16x32_bf16 v[84:87], v[154:157], v[200:203], v[84:87]
	v_mfma_f32_16x16x32_bf16 v[68:71], v[154:157], v[208:211], v[68:71]
	v_mfma_f32_16x16x32_bf16 v[76:79], v[146:149], v[208:211], v[76:79]
	v_mfma_f32_16x16x32_bf16 v[126:129], v[150:153], v[188:191], v[126:129]
	v_mfma_f32_16x16x32_bf16 v[118:121], v[162:165], v[188:191], v[118:121]
	v_mfma_f32_16x16x32_bf16 v[102:105], v[162:165], v[196:199], v[102:105]
	v_mfma_f32_16x16x32_bf16 v[110:113], v[150:153], v[196:199], v[110:113]
	v_mfma_f32_16x16x32_bf16 v[92:95], v[150:153], v[204:207], v[92:95]
	v_mfma_f32_16x16x32_bf16 v[84:87], v[162:165], v[204:207], v[84:87]
	v_mfma_f32_16x16x32_bf16 v[68:71], v[162:165], v[212:215], v[68:71]
	v_mfma_f32_16x16x32_bf16 v[76:79], v[150:153], v[212:215], v[76:79]
	s_setprio 0
	s_setprio 1
	v_mfma_f32_16x16x32_bf16 v[122:125], v[166:169], v[184:187], v[122:125]
	v_mfma_f32_16x16x32_bf16 v[114:117], v[174:177], v[184:187], v[114:117]
	v_mfma_f32_16x16x32_bf16 v[98:101], v[174:177], v[192:195], v[98:101]
	v_mfma_f32_16x16x32_bf16 v[106:109], v[166:169], v[192:195], v[106:109]
	v_mfma_f32_16x16x32_bf16 v[88:91], v[166:169], v[200:203], v[88:91]
	v_mfma_f32_16x16x32_bf16 v[80:83], v[174:177], v[200:203], v[80:83]
	v_mfma_f32_16x16x32_bf16 v[64:67], v[174:177], v[208:211], v[64:67]
	v_mfma_f32_16x16x32_bf16 v[72:75], v[166:169], v[208:211], v[72:75]
	v_mfma_f32_16x16x32_bf16 v[122:125], v[170:173], v[188:191], v[122:125]
	v_mfma_f32_16x16x32_bf16 v[114:117], v[180:183], v[188:191], v[114:117]
	v_mfma_f32_16x16x32_bf16 v[98:101], v[180:183], v[196:199], v[98:101]
	v_mfma_f32_16x16x32_bf16 v[106:109], v[170:173], v[196:199], v[106:109]
	v_mfma_f32_16x16x32_bf16 v[88:91], v[170:173], v[204:207], v[88:91]
	v_mfma_f32_16x16x32_bf16 v[80:83], v[180:183], v[204:207], v[80:83]
	v_mfma_f32_16x16x32_bf16 v[64:67], v[180:183], v[212:215], v[64:67]
	v_mfma_f32_16x16x32_bf16 v[72:75], v[170:173], v[212:215], v[72:75]
	s_setprio 0
	s_barrier
; #define PG8_BAR __builtin_amdgcn_s_barrier()
; template <class Epi, class Sched, bool ALIGN_EPI = false, bool SP2 = false>
; __device__ __forceinline__ void gemm_phase(PG8_LAS unsigned char* lds, const Gemm g, const Sched& S, const Epi& E) {
;     ...
;         if constexpr (Epi::PEEL) {
;             const char* a1 = cA + kstepA; const char* a2 = cA + 2 * kstepA; const char* b2 = cB + 2 * kstepB; const char* a3 = a2 + kstepA; const char* b3 = b2 + kstepB;
;             PG8_ITER(8);
;         }
;         for (int t = (Epi::PEEL ? 2 : 0); t < nt; t += 2) {
;             const bool last = (t == nt - 2);
;             const char* a1 = cA + (size_t)(t + 1) * kstepA;
;             const char* a2 = last ? nA : cA + (size_t)(t + 2) * kstepA; const char* b2 = last ? nB : cB + (size_t)(t + 2) * kstepB;
;             const char* a3 = a2 + kstepA; const char* b3 = b2 + kstepB;
;             PG8_ITER(8);
;         }
;     ...
;         if constexpr (ALIGN_EPI) { if (wr == 0) PG8_BAR; }
	s_mov_b32 m0, s30
	v_lshl_add_u64 v[158:159], v[158:159], 0, s[36:37]
	s_add_u32 s8, s42, 0x40080
	ds_read_b128 v[184:187], v161 offset:49152
	ds_read_b128 v[188:191], v161 offset:50176
	ds_read_b128 v[192:195], v161 offset:51200
	ds_read_b128 v[196:199], v161 offset:52224
	ds_read_b128 v[200:203], v161 offset:53248
	ds_read_b128 v[204:207], v161 offset:54272
	ds_read_b128 v[208:211], v161 offset:55296
	ds_read_b128 v[212:215], v161 offset:56320
	global_load_lds_dwordx4 v[158:159], off
	v_lshl_add_u64 v[158:159], v[178:179], 0, s[36:37]
	s_mov_b32 m0, s31
	s_addc_u32 s9, s43, 0
	global_load_lds_dwordx4 v[158:159], off
	v_lshl_add_u64 v[158:159], s[8:9], 0, v[132:133]
	s_mov_b32 m0, s57
	s_nop 0
	global_load_lds_dwordx4 v[158:159], off
	v_lshl_add_u64 v[158:159], s[8:9], 0, v[136:137]
	s_mov_b32 m0, s96
	s_nop 0
	global_load_lds_dwordx4 v[158:159], off
	v_lshl_add_u64 v[158:159], s[24:25], 0, v[130:131]
	s_mov_b32 m0, s11
	s_nop 0
	global_load_lds_dwordx4 v[158:159], off
	v_lshl_add_u64 v[158:159], s[24:25], 0, v[134:135]
	s_mov_b32 m0, s19
	s_nop 0
	global_load_lds_dwordx4 v[158:159], off
	s_sleep 2
	s_waitcnt vmcnt(8)
	s_waitcnt lgkmcnt(0)
	s_barrier
	s_setprio 1
	s_waitcnt lgkmcnt(0)
	v_mfma_f32_16x16x32_bf16 v[60:63], v[146:149], v[184:187], v[60:63]
	v_mfma_f32_16x16x32_bf16 v[52:55], v[154:157], v[184:187], v[52:55]
	v_mfma_f32_16x16x32_bf16 v[36:39], v[154:157], v[192:195], v[36:39]
	v_mfma_f32_16x16x32_bf16 v[44:47], v[146:149], v[192:195], v[44:47]
	v_mfma_f32_16x16x32_bf16 v[28:31], v[146:149], v[200:203], v[28:31]
	v_mfma_f32_16x16x32_bf16 v[20:23], v[154:157], v[200:203], v[20:23]
	v_mfma_f32_16x16x32_bf16 v[4:7], v[154:157], v[208:211], v[4:7]
	v_mfma_f32_16x16x32_bf16 v[12:15], v[146:149], v[208:211], v[12:15]
	v_mfma_f32_16x16x32_bf16 v[60:63], v[150:153], v[188:191], v[60:63]
	v_mfma_f32_16x16x32_bf16 v[52:55], v[162:165], v[188:191], v[52:55]
	v_mfma_f32_16x16x32_bf16 v[36:39], v[162:165], v[196:199], v[36:39]
	v_mfma_f32_16x16x32_bf16 v[44:47], v[150:153], v[196:199], v[44:47]
	v_mfma_f32_16x16x32_bf16 v[28:31], v[150:153], v[204:207], v[28:31]
	v_mfma_f32_16x16x32_bf16 v[20:23], v[162:165], v[204:207], v[20:23]
	v_mfma_f32_16x16x32_bf16 v[4:7], v[162:165], v[212:215], v[4:7]
	v_mfma_f32_16x16x32_bf16 v[12:15], v[150:153], v[212:215], v[12:15]
	s_setprio 0
	s_setprio 1
	v_mfma_f32_16x16x32_bf16 v[56:59], v[166:169], v[184:187], v[56:59]
	v_mfma_f32_16x16x32_bf16 v[48:51], v[174:177], v[184:187], v[48:51]
	v_mfma_f32_16x16x32_bf16 v[32:35], v[174:177], v[192:195], v[32:35]
	v_mfma_f32_16x16x32_bf16 v[40:43], v[166:169], v[192:195], v[40:43]
	v_mfma_f32_16x16x32_bf16 v[24:27], v[166:169], v[200:203], v[24:27]
	v_mfma_f32_16x16x32_bf16 v[16:19], v[174:177], v[200:203], v[16:19]
	v_mfma_f32_16x16x32_bf16 v[0:3], v[174:177], v[208:211], v[0:3]
	v_mfma_f32_16x16x32_bf16 v[8:11], v[166:169], v[208:211], v[8:11]
	v_mfma_f32_16x16x32_bf16 v[56:59], v[170:173], v[188:191], v[56:59]
	v_mfma_f32_16x16x32_bf16 v[48:51], v[180:183], v[188:191], v[48:51]
	v_mfma_f32_16x16x32_bf16 v[32:35], v[180:183], v[196:199], v[32:35]
	v_mfma_f32_16x16x32_bf16 v[40:43], v[170:173], v[196:199], v[40:43]
	v_mfma_f32_16x16x32_bf16 v[24:27], v[170:173], v[204:207], v[24:27]
	v_mfma_f32_16x16x32_bf16 v[16:19], v[180:183], v[204:207], v[16:19]
	v_mfma_f32_16x16x32_bf16 v[0:3], v[180:183], v[212:215], v[0:3]
	v_mfma_f32_16x16x32_bf16 v[8:11], v[170:173], v[212:215], v[8:11]
	s_setprio 0
	s_barrier
	s_add_i32 s18, s18, 2
	s_add_u32 s3, s3, 0x100
	s_addc_u32 s2, s2, 0
	s_add_u32 s0, s0, 0x800000
	s_addc_u32 s1, s1, 0
	s_cmp_gt_u32 s18, 13
	s_cbranch_scc0 .LBB0_161
	v_readlane_b32 s0, v255, 45
	v_readlane_b32 s1, v255, 46
	s_and_b64 vcc, exec, s[0:1]
	s_cbranch_vccz .LBB0_164
	s_barrier

; template <class Epi, class Sched, bool ALIGN_EPI = false, bool SP2 = false>
; __device__ __forceinline__ void gemm_phase(PG8_LAS unsigned char* lds, const Gemm g, const Sched& S, const Epi& E) {
;     ...
;         if constexpr (Epi::PEEL) {
;             const char* a1 = cA + kstepA; const char* a2 = cA + 2 * kstepA; const char* b2 = cB + 2 * kstepB; const char* a3 = a2 + kstepA; const char* b3 = b2 + kstepB;
;             PG8_ITER(8);
;         }
;         for (int t = (Epi::PEEL ? 2 : 0); t < nt; t += 2) {
;             const bool last = (t == nt - 2);
;             const char* a1 = cA + (size_t)(t + 1) * kstepA;
;             const char* a2 = last ? nA : cA + (size_t)(t + 2) * kstepA; const char* b2 = last ? nB : cB + (size_t)(t + 2) * kstepB;
;             const char* a3 = a2 + kstepA; const char* b3 = b2 + kstepB;
;             PG8_ITER(8);
.LBB0_250:
	ds_read_b128 v[146:149], v130
	ds_read_b128 v[152:155], v130 offset:1024
	ds_read_b128 v[156:159], v130 offset:2048
	ds_read_b128 v[160:163], v130 offset:3072
	ds_read_b128 v[164:167], v131
	ds_read_b128 v[168:171], v131 offset:1024
	ds_read_b128 v[172:175], v131 offset:2048
	ds_read_b128 v[180:183], v131 offset:3072
	s_add_u32 s16, s24, 0x3fc000
	s_addc_u32 s17, s25, 0
	s_cmp_eq_u32 s18, 12
	s_cselect_b32 s28, s47, s16
	s_cselect_b32 s29, s27, s17
	s_cselect_b32 s44, s54, s3
	s_cselect_b32 s45, s49, s2
	s_add_u32 s42, s28, 0x400000
	s_addc_u32 s43, s29, 0
	s_mov_b32 m0, s55
	v_lshl_add_u64 v[176:177], s[24:25], 0, v[144:145]
	ds_read_b128 v[184:187], v151
	ds_read_b128 v[188:191], v151 offset:1024
	ds_read_b128 v[192:195], v151 offset:2048
	ds_read_b128 v[196:199], v151 offset:3072
	ds_read_b128 v[200:203], v151 offset:4096
	ds_read_b128 v[204:207], v151 offset:5120
	ds_read_b128 v[208:211], v151 offset:6144
	ds_read_b128 v[212:215], v151 offset:7168
	global_load_lds_dwordx4 v[176:177], off
	v_lshl_add_u64 v[176:177], s[24:25], 0, v[142:143]
	s_mov_b32 m0, s98
	s_nop 0
	global_load_lds_dwordx4 v[176:177], off
	s_sleep 2
	s_waitcnt vmcnt(8)
	s_waitcnt lgkmcnt(0)
	s_barrier
	s_setprio 1
	s_waitcnt lgkmcnt(0)
	v_mfma_f32_16x16x32_bf16 v[118:121], v[146:149], v[184:187], v[118:121]
	v_mfma_f32_16x16x32_bf16 v[114:117], v[156:159], v[184:187], v[114:117]
	v_mfma_f32_16x16x32_bf16 v[98:101], v[156:159], v[192:195], v[98:101]
	v_mfma_f32_16x16x32_bf16 v[102:105], v[146:149], v[192:195], v[102:105]
	v_mfma_f32_16x16x32_bf16 v[84:87], v[146:149], v[200:203], v[84:87]
	v_mfma_f32_16x16x32_bf16 v[80:83], v[156:159], v[200:203], v[80:83]
	v_mfma_f32_16x16x32_bf16 v[64:67], v[156:159], v[208:211], v[64:67]
	v_mfma_f32_16x16x32_bf16 v[68:71], v[146:149], v[208:211], v[68:71]
	v_mfma_f32_16x16x32_bf16 v[118:121], v[152:155], v[188:191], v[118:121]
	v_mfma_f32_16x16x32_bf16 v[114:117], v[160:163], v[188:191], v[114:117]
	v_mfma_f32_16x16x32_bf16 v[98:101], v[160:163], v[196:199], v[98:101]
	v_mfma_f32_16x16x32_bf16 v[102:105], v[152:155], v[196:199], v[102:105]
	v_mfma_f32_16x16x32_bf16 v[84:87], v[152:155], v[204:207], v[84:87]
	v_mfma_f32_16x16x32_bf16 v[80:83], v[160:163], v[204:207], v[80:83]
	v_mfma_f32_16x16x32_bf16 v[64:67], v[160:163], v[212:215], v[64:67]
	v_mfma_f32_16x16x32_bf16 v[68:71], v[152:155], v[212:215], v[68:71]
	s_setprio 0
	s_setprio 1
	v_mfma_f32_16x16x32_bf16 v[126:129], v[164:167], v[184:187], v[126:129]
	v_mfma_f32_16x16x32_bf16 v[122:125], v[172:175], v[184:187], v[122:125]
	v_mfma_f32_16x16x32_bf16 v[106:109], v[172:175], v[192:195], v[106:109]
	v_mfma_f32_16x16x32_bf16 v[110:113], v[164:167], v[192:195], v[110:113]
	v_mfma_f32_16x16x32_bf16 v[92:95], v[164:167], v[200:203], v[92:95]
	v_mfma_f32_16x16x32_bf16 v[88:91], v[172:175], v[200:203], v[88:91]
	v_mfma_f32_16x16x32_bf16 v[72:75], v[172:175], v[208:211], v[72:75]
	v_mfma_f32_16x16x32_bf16 v[76:79], v[164:167], v[208:211], v[76:79]
	v_mfma_f32_16x16x32_bf16 v[126:129], v[168:171], v[188:191], v[126:129]
	v_mfma_f32_16x16x32_bf16 v[122:125], v[180:183], v[188:191], v[122:125]
	v_mfma_f32_16x16x32_bf16 v[106:109], v[180:183], v[196:199], v[106:109]
	v_mfma_f32_16x16x32_bf16 v[110:113], v[168:171], v[196:199], v[110:113]
	v_mfma_f32_16x16x32_bf16 v[92:95], v[168:171], v[204:207], v[92:95]
	v_mfma_f32_16x16x32_bf16 v[88:91], v[180:183], v[204:207], v[88:91]
	v_mfma_f32_16x16x32_bf16 v[72:75], v[180:183], v[212:215], v[72:75]
	v_mfma_f32_16x16x32_bf16 v[76:79], v[168:171], v[212:215], v[76:79]
	s_setprio 0
	s_barrier
	s_mov_b32 m0, s99
	v_lshl_add_u64 v[176:177], s[44:45], 0, v[136:137]
	s_add_u32 s16, s44, 0x40000
	ds_read_b128 v[184:187], v151 offset:16384
	ds_read_b128 v[188:191], v151 offset:17408
	ds_read_b128 v[192:195], v151 offset:18432
	ds_read_b128 v[196:199], v151 offset:19456
	ds_read_b128 v[200:203], v151 offset:20480
	ds_read_b128 v[204:207], v151 offset:21504
	ds_read_b128 v[208:211], v151 offset:22528
	ds_read_b128 v[212:215], v151 offset:23552
	global_load_lds_dwordx4 v[176:177], off
	v_lshl_add_u64 v[178:179], s[44:45], 0, v[140:141]
	s_mov_b32 m0, vcc_lo
	s_addc_u32 s17, s45, 0
	global_load_lds_dwordx4 v[178:179], off
	v_lshl_add_u64 v[216:217], s[16:17], 0, v[136:137]
	s_mov_b32 m0, vcc_hi
	s_nop 0
	global_load_lds_dwordx4 v[216:217], off
	v_lshl_add_u64 v[216:217], s[16:17], 0, v[140:141]
	s_mov_b32 m0, s30
	s_nop 0
	global_load_lds_dwordx4 v[216:217], off
	v_lshl_add_u64 v[216:217], s[28:29], 0, v[134:135]
	s_mov_b32 m0, s22
	s_nop 0
	global_load_lds_dwordx4 v[216:217], off
	v_lshl_add_u64 v[216:217], s[28:29], 0, v[138:139]
	s_mov_b32 m0, s23
	s_nop 0
	global_load_lds_dwordx4 v[216:217], off
	s_sleep 2
	s_waitcnt vmcnt(8)
	s_waitcnt lgkmcnt(0)
	s_barrier
	s_setprio 1
	s_waitcnt lgkmcnt(0)
	v_mfma_f32_16x16x32_bf16 v[52:55], v[146:149], v[184:187], v[52:55]
	v_mfma_f32_16x16x32_bf16 v[48:51], v[156:159], v[184:187], v[48:51]
	v_mfma_f32_16x16x32_bf16 v[32:35], v[156:159], v[192:195], v[32:35]
	v_mfma_f32_16x16x32_bf16 v[36:39], v[146:149], v[192:195], v[36:39]
	v_mfma_f32_16x16x32_bf16 v[20:23], v[146:149], v[200:203], v[20:23]
	v_mfma_f32_16x16x32_bf16 v[16:19], v[156:159], v[200:203], v[16:19]
	v_mfma_f32_16x16x32_bf16 v[0:3], v[156:159], v[208:211], v[0:3]
	v_mfma_f32_16x16x32_bf16 v[4:7], v[146:149], v[208:211], v[4:7]
	v_mfma_f32_16x16x32_bf16 v[52:55], v[152:155], v[188:191], v[52:55]
	v_mfma_f32_16x16x32_bf16 v[48:51], v[160:163], v[188:191], v[48:51]
	v_mfma_f32_16x16x32_bf16 v[32:35], v[160:163], v[196:199], v[32:35]
	v_mfma_f32_16x16x32_bf16 v[36:39], v[152:155], v[196:199], v[36:39]
	v_mfma_f32_16x16x32_bf16 v[20:23], v[152:155], v[204:207], v[20:23]
	v_mfma_f32_16x16x32_bf16 v[16:19], v[160:163], v[204:207], v[16:19]
	v_mfma_f32_16x16x32_bf16 v[0:3], v[160:163], v[212:215], v[0:3]
	v_mfma_f32_16x16x32_bf16 v[4:7], v[152:155], v[212:215], v[4:7]
	s_setprio 0
	s_setprio 1
	v_mfma_f32_16x16x32_bf16 v[60:63], v[164:167], v[184:187], v[60:63]
	v_mfma_f32_16x16x32_bf16 v[56:59], v[172:175], v[184:187], v[56:59]
	v_mfma_f32_16x16x32_bf16 v[40:43], v[172:175], v[192:195], v[40:43]
	v_mfma_f32_16x16x32_bf16 v[44:47], v[164:167], v[192:195], v[44:47]
	v_mfma_f32_16x16x32_bf16 v[28:31], v[164:167], v[200:203], v[28:31]
	v_mfma_f32_16x16x32_bf16 v[24:27], v[172:175], v[200:203], v[24:27]
	v_mfma_f32_16x16x32_bf16 v[8:11], v[172:175], v[208:211], v[8:11]
	v_mfma_f32_16x16x32_bf16 v[12:15], v[164:167], v[208:211], v[12:15]
	v_mfma_f32_16x16x32_bf16 v[60:63], v[168:171], v[188:191], v[60:63]
	v_mfma_f32_16x16x32_bf16 v[56:59], v[180:183], v[188:191], v[56:59]
	v_mfma_f32_16x16x32_bf16 v[40:43], v[180:183], v[196:199], v[40:43]
	v_mfma_f32_16x16x32_bf16 v[44:47], v[168:171], v[196:199], v[44:47]
	v_mfma_f32_16x16x32_bf16 v[28:31], v[168:171], v[204:207], v[28:31]
	v_mfma_f32_16x16x32_bf16 v[24:27], v[180:183], v[204:207], v[24:27]
	v_mfma_f32_16x16x32_bf16 v[8:11], v[180:183], v[212:215], v[8:11]
	v_mfma_f32_16x16x32_bf16 v[12:15], v[168:171], v[212:215], v[12:15]
	s_setprio 0
	s_barrier
	ds_read_b128 v[146:149], v132
	ds_read_b128 v[152:155], v132 offset:1024
	ds_read_b128 v[156:159], v132 offset:2048
	ds_read_b128 v[160:163], v132 offset:3072
	ds_read_b128 v[164:167], v133
	ds_read_b128 v[168:171], v133 offset:1024
	ds_read_b128 v[172:175], v133 offset:2048
	ds_read_b128 v[180:183], v133 offset:3072
	s_add_u32 s16, s28, 0x4000
	s_addc_u32 s17, s29, 0
	s_mov_b32 m0, s39
	v_lshl_add_u64 v[216:217], s[16:17], 0, v[134:135]
	ds_read_b128 v[184:187], v151 offset:32768
	ds_read_b128 v[188:191], v151 offset:33792
	ds_read_b128 v[192:195], v151 offset:34816
	ds_read_b128 v[196:199], v151 offset:35840
	ds_read_b128 v[200:203], v151 offset:36864
	ds_read_b128 v[204:207], v151 offset:37888
	ds_read_b128 v[208:211], v151 offset:38912
	ds_read_b128 v[212:215], v151 offset:39936
	global_load_lds_dwordx4 v[216:217], off
	v_lshl_add_u64 v[216:217], s[16:17], 0, v[138:139]
	s_mov_b32 m0, s56
	s_nop 0
	global_load_lds_dwordx4 v[216:217], off
	s_sleep 2
	s_waitcnt vmcnt(8)
	s_waitcnt lgkmcnt(0)
	s_barrier
	s_setprio 1
	s_waitcnt lgkmcnt(0)
	v_mfma_f32_16x16x32_bf16 v[118:121], v[146:149], v[184:187], v[118:121]
	v_mfma_f32_16x16x32_bf16 v[114:117], v[156:159], v[184:187], v[114:117]
	v_mfma_f32_16x16x32_bf16 v[98:101], v[156:159], v[192:195], v[98:101]
	v_mfma_f32_16x16x32_bf16 v[102:105], v[146:149], v[192:195], v[102:105]
	v_mfma_f32_16x16x32_bf16 v[84:87], v[146:149], v[200:203], v[84:87]
	v_mfma_f32_16x16x32_bf16 v[80:83], v[156:159], v[200:203], v[80:83]
	v_mfma_f32_16x16x32_bf16 v[64:67], v[156:159], v[208:211], v[64:67]
	v_mfma_f32_16x16x32_bf16 v[68:71], v[146:149], v[208:211], v[68:71]
	v_mfma_f32_16x16x32_bf16 v[118:121], v[152:155], v[188:191], v[118:121]
	v_mfma_f32_16x16x32_bf16 v[114:117], v[160:163], v[188:191], v[114:117]
	v_mfma_f32_16x16x32_bf16 v[98:101], v[160:163], v[196:199], v[98:101]
	v_mfma_f32_16x16x32_bf16 v[102:105], v[152:155], v[196:199], v[102:105]
	v_mfma_f32_16x16x32_bf16 v[84:87], v[152:155], v[204:207], v[84:87]
	v_mfma_f32_16x16x32_bf16 v[80:83], v[160:163], v[204:207], v[80:83]
	v_mfma_f32_16x16x32_bf16 v[64:67], v[160:163], v[212:215], v[64:67]
	v_mfma_f32_16x16x32_bf16 v[68:71], v[152:155], v[212:215], v[68:71]
	s_setprio 0
	s_setprio 1
	v_mfma_f32_16x16x32_bf16 v[126:129], v[164:167], v[184:187], v[126:129]
	v_mfma_f32_16x16x32_bf16 v[122:125], v[172:175], v[184:187], v[122:125]
	v_mfma_f32_16x16x32_bf16 v[106:109], v[172:175], v[192:195], v[106:109]
	v_mfma_f32_16x16x32_bf16 v[110:113], v[164:167], v[192:195], v[110:113]
	v_mfma_f32_16x16x32_bf16 v[92:95], v[164:167], v[200:203], v[92:95]
	v_mfma_f32_16x16x32_bf16 v[88:91], v[172:175], v[200:203], v[88:91]
	v_mfma_f32_16x16x32_bf16 v[72:75], v[172:175], v[208:211], v[72:75]
	v_mfma_f32_16x16x32_bf16 v[76:79], v[164:167], v[208:211], v[76:79]
	v_mfma_f32_16x16x32_bf16 v[126:129], v[168:171], v[188:191], v[126:129]
	v_mfma_f32_16x16x32_bf16 v[122:125], v[180:183], v[188:191], v[122:125]
	v_mfma_f32_16x16x32_bf16 v[106:109], v[180:183], v[196:199], v[106:109]
	v_mfma_f32_16x16x32_bf16 v[110:113], v[168:171], v[196:199], v[110:113]
	v_mfma_f32_16x16x32_bf16 v[92:95], v[168:171], v[204:207], v[92:95]
	v_mfma_f32_16x16x32_bf16 v[88:91], v[180:183], v[204:207], v[88:91]
	v_mfma_f32_16x16x32_bf16 v[72:75], v[180:183], v[212:215], v[72:75]
	v_mfma_f32_16x16x32_bf16 v[76:79], v[168:171], v[212:215], v[76:79]
	s_setprio 0
	s_barrier
; #define PG8_BAR __builtin_amdgcn_s_barrier()
; template <class Epi, class Sched, bool ALIGN_EPI = false, bool SP2 = false>
; __device__ __forceinline__ void gemm_phase(PG8_LAS unsigned char* lds, const Gemm g, const Sched& S, const Epi& E) {
;     ...
;         if constexpr (Epi::PEEL) {
;             const char* a1 = cA + kstepA; const char* a2 = cA + 2 * kstepA; const char* b2 = cB + 2 * kstepB; const char* a3 = a2 + kstepA; const char* b3 = b2 + kstepB;
;             PG8_ITER(8);
;         }
;         for (int t = (Epi::PEEL ? 2 : 0); t < nt; t += 2) {
;             const bool last = (t == nt - 2);
;             const char* a1 = cA + (size_t)(t + 1) * kstepA;
;             const char* a2 = last ? nA : cA + (size_t)(t + 2) * kstepA; const char* b2 = last ? nB : cB + (size_t)(t + 2) * kstepB;
;             const char* a3 = a2 + kstepA; const char* b3 = b2 + kstepB;
;             PG8_ITER(8);
;         }
;     ...
;         if constexpr (ALIGN_EPI) { if (wr == 0) PG8_BAR; }
	s_mov_b32 m0, s31
	v_lshl_add_u64 v[176:177], v[176:177], 0, s[36:37]
	s_add_u32 s16, s44, 0x40080
	ds_read_b128 v[184:187], v151 offset:49152
	ds_read_b128 v[188:191], v151 offset:50176
	ds_read_b128 v[192:195], v151 offset:51200
	ds_read_b128 v[196:199], v151 offset:52224
	ds_read_b128 v[200:203], v151 offset:53248
	ds_read_b128 v[204:207], v151 offset:54272
	ds_read_b128 v[208:211], v151 offset:55296
	ds_read_b128 v[212:215], v151 offset:56320
	global_load_lds_dwordx4 v[176:177], off
	v_lshl_add_u64 v[176:177], v[178:179], 0, s[36:37]
	s_mov_b32 m0, s12
	s_addc_u32 s17, s45, 0
	global_load_lds_dwordx4 v[176:177], off
	v_lshl_add_u64 v[176:177], s[16:17], 0, v[136:137]
	s_mov_b32 m0, s13
	s_nop 0
	global_load_lds_dwordx4 v[176:177], off
	v_lshl_add_u64 v[176:177], s[16:17], 0, v[140:141]
	s_mov_b32 m0, s11
	s_nop 0
	global_load_lds_dwordx4 v[176:177], off
	v_lshl_add_u64 v[176:177], s[42:43], 0, v[134:135]
	s_mov_b32 m0, s59
	s_nop 0
	global_load_lds_dwordx4 v[176:177], off
	v_lshl_add_u64 v[176:177], s[42:43], 0, v[138:139]
	s_mov_b32 m0, s96
	s_nop 0
	global_load_lds_dwordx4 v[176:177], off
	s_sleep 2
	s_waitcnt vmcnt(8)
	s_waitcnt lgkmcnt(0)
	s_barrier
	s_setprio 1
	s_waitcnt lgkmcnt(0)
	v_mfma_f32_16x16x32_bf16 v[52:55], v[146:149], v[184:187], v[52:55]
	v_mfma_f32_16x16x32_bf16 v[48:51], v[156:159], v[184:187], v[48:51]
	v_mfma_f32_16x16x32_bf16 v[32:35], v[156:159], v[192:195], v[32:35]
	v_mfma_f32_16x16x32_bf16 v[36:39], v[146:149], v[192:195], v[36:39]
	v_mfma_f32_16x16x32_bf16 v[20:23], v[146:149], v[200:203], v[20:23]
	v_mfma_f32_16x16x32_bf16 v[16:19], v[156:159], v[200:203], v[16:19]
	v_mfma_f32_16x16x32_bf16 v[0:3], v[156:159], v[208:211], v[0:3]
	v_mfma_f32_16x16x32_bf16 v[4:7], v[146:149], v[208:211], v[4:7]
	v_mfma_f32_16x16x32_bf16 v[52:55], v[152:155], v[188:191], v[52:55]
	v_mfma_f32_16x16x32_bf16 v[48:51], v[160:163], v[188:191], v[48:51]
	v_mfma_f32_16x16x32_bf16 v[32:35], v[160:163], v[196:199], v[32:35]
	v_mfma_f32_16x16x32_bf16 v[36:39], v[152:155], v[196:199], v[36:39]
	v_mfma_f32_16x16x32_bf16 v[20:23], v[152:155], v[204:207], v[20:23]
	v_mfma_f32_16x16x32_bf16 v[16:19], v[160:163], v[204:207], v[16:19]
	v_mfma_f32_16x16x32_bf16 v[0:3], v[160:163], v[212:215], v[0:3]
	v_mfma_f32_16x16x32_bf16 v[4:7], v[152:155], v[212:215], v[4:7]
	s_setprio 0
	s_setprio 1
	v_mfma_f32_16x16x32_bf16 v[60:63], v[164:167], v[184:187], v[60:63]
	v_mfma_f32_16x16x32_bf16 v[56:59], v[172:175], v[184:187], v[56:59]
	v_mfma_f32_16x16x32_bf16 v[40:43], v[172:175], v[192:195], v[40:43]
	v_mfma_f32_16x16x32_bf16 v[44:47], v[164:167], v[192:195], v[44:47]
	v_mfma_f32_16x16x32_bf16 v[28:31], v[164:167], v[200:203], v[28:31]
	v_mfma_f32_16x16x32_bf16 v[24:27], v[172:175], v[200:203], v[24:27]
	v_mfma_f32_16x16x32_bf16 v[8:11], v[172:175], v[208:211], v[8:11]
	v_mfma_f32_16x16x32_bf16 v[12:15], v[164:167], v[208:211], v[12:15]
	v_mfma_f32_16x16x32_bf16 v[60:63], v[168:171], v[188:191], v[60:63]
	v_mfma_f32_16x16x32_bf16 v[56:59], v[180:183], v[188:191], v[56:59]
	v_mfma_f32_16x16x32_bf16 v[40:43], v[180:183], v[196:199], v[40:43]
	v_mfma_f32_16x16x32_bf16 v[44:47], v[168:171], v[196:199], v[44:47]
	v_mfma_f32_16x16x32_bf16 v[28:31], v[168:171], v[204:207], v[28:31]
	v_mfma_f32_16x16x32_bf16 v[24:27], v[180:183], v[204:207], v[24:27]
	v_mfma_f32_16x16x32_bf16 v[8:11], v[180:183], v[212:215], v[8:11]
	v_mfma_f32_16x16x32_bf16 v[12:15], v[168:171], v[212:215], v[12:15]
	s_setprio 0
	s_barrier
	s_add_i32 s18, s18, 2
	s_add_u32 s3, s3, 0x100
	s_addc_u32 s2, s2, 0
	s_add_u32 s24, s24, 0x800000
	s_addc_u32 s25, s25, 0
	s_cmp_gt_u32 s18, 13
	s_cbranch_scc0 .LBB0_250
	v_readlane_b32 s2, v255, 33
	v_readlane_b32 s3, v255, 34
	v_readlane_b32 s12, v255, 31
	s_and_b64 vcc, exec, s[2:3]
	v_readlane_b32 s13, v255, 32
	s_cbranch_vccz .LBB0_253
	s_barrier

; template <class Epi, class Sched, bool ALIGN_EPI = false, bool SP2 = false>
; __device__ __forceinline__ void gemm_phase(PG8_LAS unsigned char* lds, const Gemm g, const Sched& S, const Epi& E) {
;     ...
;         if constexpr (Epi::PEEL) {
;             const char* a1 = cA + kstepA; const char* a2 = cA + 2 * kstepA; const char* b2 = cB + 2 * kstepB; const char* a3 = a2 + kstepA; const char* b3 = b2 + kstepB;
;             PG8_ITER(8);
;         }
;         for (int t = (Epi::PEEL ? 2 : 0); t < nt; t += 2) {
;             const bool last = (t == nt - 2);
;             const char* a1 = cA + (size_t)(t + 1) * kstepA;
;             const char* a2 = last ? nA : cA + (size_t)(t + 2) * kstepA; const char* b2 = last ? nB : cB + (size_t)(t + 2) * kstepB;
;             const char* a3 = a2 + kstepA; const char* b3 = b2 + kstepB;
;             PG8_ITER(8);
.LBB0_478:
	ds_read_b128 v[146:149], v142
	ds_read_b128 v[150:153], v142 offset:1024
	ds_read_b128 v[158:161], v142 offset:2048
	ds_read_b128 v[162:165], v142 offset:3072
	ds_read_b128 v[166:169], v143
	ds_read_b128 v[170:173], v143 offset:1024
	ds_read_b128 v[174:177], v143 offset:2048
	ds_read_b128 v[180:183], v143 offset:3072
	s_add_u32 s10, s0, 0x3fc000
	s_addc_u32 s11, s1, 0
	s_cmp_eq_u32 s18, 12
	s_cselect_b32 s44, s27, s10
	s_cselect_b32 s45, s25, s11
	s_cselect_b32 s42, s58, s3
	s_cselect_b32 s43, s57, s2
	s_add_u32 s34, s44, 0x400000
	s_addc_u32 s35, s45, 0
	s_mov_b32 m0, s59
	v_lshl_add_u64 v[154:155], s[0:1], 0, v[140:141]
	ds_read_b128 v[184:187], v156
	ds_read_b128 v[188:191], v156 offset:1024
	ds_read_b128 v[192:195], v156 offset:2048
	ds_read_b128 v[196:199], v156 offset:3072
	ds_read_b128 v[200:203], v156 offset:4096
	ds_read_b128 v[204:207], v156 offset:5120
	ds_read_b128 v[208:211], v156 offset:6144
	ds_read_b128 v[212:215], v156 offset:7168
	global_load_lds_dwordx4 v[154:155], off
	v_lshl_add_u64 v[154:155], s[0:1], 0, v[138:139]
	s_mov_b32 m0, s60
	s_nop 0
	global_load_lds_dwordx4 v[154:155], off
	s_sleep 2
	s_waitcnt vmcnt(8)
	s_waitcnt lgkmcnt(0)
	s_barrier
	s_setprio 1
	s_waitcnt lgkmcnt(0)
	v_mfma_f32_16x16x32_bf16 v[122:125], v[146:149], v[184:187], v[122:125]
	v_mfma_f32_16x16x32_bf16 v[114:117], v[158:161], v[184:187], v[114:117]
	v_mfma_f32_16x16x32_bf16 v[98:101], v[158:161], v[192:195], v[98:101]
	v_mfma_f32_16x16x32_bf16 v[106:109], v[146:149], v[192:195], v[106:109]
	v_mfma_f32_16x16x32_bf16 v[88:91], v[146:149], v[200:203], v[88:91]
	v_mfma_f32_16x16x32_bf16 v[80:83], v[158:161], v[200:203], v[80:83]
	v_mfma_f32_16x16x32_bf16 v[60:63], v[158:161], v[208:211], v[60:63]
	v_mfma_f32_16x16x32_bf16 v[72:75], v[146:149], v[208:211], v[72:75]
	v_mfma_f32_16x16x32_bf16 v[122:125], v[150:153], v[188:191], v[122:125]
	v_mfma_f32_16x16x32_bf16 v[114:117], v[162:165], v[188:191], v[114:117]
	v_mfma_f32_16x16x32_bf16 v[98:101], v[162:165], v[196:199], v[98:101]
	v_mfma_f32_16x16x32_bf16 v[106:109], v[150:153], v[196:199], v[106:109]
	v_mfma_f32_16x16x32_bf16 v[88:91], v[150:153], v[204:207], v[88:91]
	v_mfma_f32_16x16x32_bf16 v[80:83], v[162:165], v[204:207], v[80:83]
	v_mfma_f32_16x16x32_bf16 v[60:63], v[162:165], v[212:215], v[60:63]
	v_mfma_f32_16x16x32_bf16 v[72:75], v[150:153], v[212:215], v[72:75]
	s_setprio 0
	s_setprio 1
	v_mfma_f32_16x16x32_bf16 v[126:129], v[166:169], v[184:187], v[126:129]
	v_mfma_f32_16x16x32_bf16 v[118:121], v[174:177], v[184:187], v[118:121]
	v_mfma_f32_16x16x32_bf16 v[102:105], v[174:177], v[192:195], v[102:105]
	v_mfma_f32_16x16x32_bf16 v[110:113], v[166:169], v[192:195], v[110:113]
	v_mfma_f32_16x16x32_bf16 v[92:95], v[166:169], v[200:203], v[92:95]
	v_mfma_f32_16x16x32_bf16 v[84:87], v[174:177], v[200:203], v[84:87]
	v_mfma_f32_16x16x32_bf16 v[68:71], v[174:177], v[208:211], v[68:71]
	v_mfma_f32_16x16x32_bf16 v[76:79], v[166:169], v[208:211], v[76:79]
	v_mfma_f32_16x16x32_bf16 v[126:129], v[170:173], v[188:191], v[126:129]
	v_mfma_f32_16x16x32_bf16 v[118:121], v[180:183], v[188:191], v[118:121]
	v_mfma_f32_16x16x32_bf16 v[102:105], v[180:183], v[196:199], v[102:105]
	v_mfma_f32_16x16x32_bf16 v[110:113], v[170:173], v[196:199], v[110:113]
	v_mfma_f32_16x16x32_bf16 v[92:95], v[170:173], v[204:207], v[92:95]
	v_mfma_f32_16x16x32_bf16 v[84:87], v[180:183], v[204:207], v[84:87]
	v_mfma_f32_16x16x32_bf16 v[68:71], v[180:183], v[212:215], v[68:71]
	v_mfma_f32_16x16x32_bf16 v[76:79], v[170:173], v[212:215], v[76:79]
	s_setprio 0
	s_barrier
	s_mov_b32 m0, s61
	v_lshl_add_u64 v[154:155], s[42:43], 0, v[132:133]
	s_add_u32 s10, s42, 0x40000
	ds_read_b128 v[184:187], v156 offset:16384
	ds_read_b128 v[188:191], v156 offset:17408
	ds_read_b128 v[192:195], v156 offset:18432
	ds_read_b128 v[196:199], v156 offset:19456
	ds_read_b128 v[200:203], v156 offset:20480
	ds_read_b128 v[204:207], v156 offset:21504
	ds_read_b128 v[208:211], v156 offset:22528
	ds_read_b128 v[212:215], v156 offset:23552
	global_load_lds_dwordx4 v[154:155], off
	v_lshl_add_u64 v[178:179], s[42:43], 0, v[136:137]
	s_mov_b32 m0, s96
	s_addc_u32 s11, s43, 0
	global_load_lds_dwordx4 v[178:179], off
	v_lshl_add_u64 v[216:217], s[10:11], 0, v[132:133]
	s_mov_b32 m0, s97
	s_nop 0
	global_load_lds_dwordx4 v[216:217], off
	v_lshl_add_u64 v[216:217], s[10:11], 0, v[136:137]
	s_mov_b32 m0, s98
	s_nop 0
	global_load_lds_dwordx4 v[216:217], off
	v_lshl_add_u64 v[216:217], s[44:45], 0, v[130:131]
	s_mov_b32 m0, s23
	s_nop 0
	global_load_lds_dwordx4 v[216:217], off
	v_lshl_add_u64 v[216:217], s[44:45], 0, v[134:135]
	s_mov_b32 m0, s39
	s_nop 0
	global_load_lds_dwordx4 v[216:217], off
	s_sleep 2
	s_waitcnt vmcnt(8)
	s_waitcnt lgkmcnt(0)
	s_barrier
	s_setprio 1
	s_waitcnt lgkmcnt(0)
	v_mfma_f32_16x16x32_bf16 v[56:59], v[146:149], v[184:187], v[56:59]
	v_mfma_f32_16x16x32_bf16 v[48:51], v[158:161], v[184:187], v[48:51]
	v_mfma_f32_16x16x32_bf16 v[32:35], v[158:161], v[192:195], v[32:35]
	v_mfma_f32_16x16x32_bf16 v[40:43], v[146:149], v[192:195], v[40:43]
	v_mfma_f32_16x16x32_bf16 v[24:27], v[146:149], v[200:203], v[24:27]
	v_mfma_f32_16x16x32_bf16 v[16:19], v[158:161], v[200:203], v[16:19]
	v_mfma_f32_16x16x32_bf16 v[0:3], v[158:161], v[208:211], v[0:3]
	v_mfma_f32_16x16x32_bf16 v[8:11], v[146:149], v[208:211], v[8:11]
	v_mfma_f32_16x16x32_bf16 v[56:59], v[150:153], v[188:191], v[56:59]
	v_mfma_f32_16x16x32_bf16 v[48:51], v[162:165], v[188:191], v[48:51]
	v_mfma_f32_16x16x32_bf16 v[32:35], v[162:165], v[196:199], v[32:35]
	v_mfma_f32_16x16x32_bf16 v[40:43], v[150:153], v[196:199], v[40:43]
	v_mfma_f32_16x16x32_bf16 v[24:27], v[150:153], v[204:207], v[24:27]
	v_mfma_f32_16x16x32_bf16 v[16:19], v[162:165], v[204:207], v[16:19]
	v_mfma_f32_16x16x32_bf16 v[0:3], v[162:165], v[212:215], v[0:3]
	v_mfma_f32_16x16x32_bf16 v[8:11], v[150:153], v[212:215], v[8:11]
	s_setprio 0
	s_setprio 1
	v_mfma_f32_16x16x32_bf16 v[64:67], v[166:169], v[184:187], v[64:67]
	v_mfma_f32_16x16x32_bf16 v[52:55], v[174:177], v[184:187], v[52:55]
	v_mfma_f32_16x16x32_bf16 v[36:39], v[174:177], v[192:195], v[36:39]
	v_mfma_f32_16x16x32_bf16 v[44:47], v[166:169], v[192:195], v[44:47]
	v_mfma_f32_16x16x32_bf16 v[28:31], v[166:169], v[200:203], v[28:31]
	v_mfma_f32_16x16x32_bf16 v[20:23], v[174:177], v[200:203], v[20:23]
	v_mfma_f32_16x16x32_bf16 v[4:7], v[174:177], v[208:211], v[4:7]
	v_mfma_f32_16x16x32_bf16 v[12:15], v[166:169], v[208:211], v[12:15]
	v_mfma_f32_16x16x32_bf16 v[64:67], v[170:173], v[188:191], v[64:67]
	v_mfma_f32_16x16x32_bf16 v[52:55], v[180:183], v[188:191], v[52:55]
	v_mfma_f32_16x16x32_bf16 v[36:39], v[180:183], v[196:199], v[36:39]
	v_mfma_f32_16x16x32_bf16 v[44:47], v[170:173], v[196:199], v[44:47]
	v_mfma_f32_16x16x32_bf16 v[28:31], v[170:173], v[204:207], v[28:31]
	v_mfma_f32_16x16x32_bf16 v[20:23], v[180:183], v[204:207], v[20:23]
	v_mfma_f32_16x16x32_bf16 v[4:7], v[180:183], v[212:215], v[4:7]
	v_mfma_f32_16x16x32_bf16 v[12:15], v[170:173], v[212:215], v[12:15]
	s_setprio 0
	s_barrier
	ds_read_b128 v[146:149], v144
	ds_read_b128 v[150:153], v144 offset:1024
	ds_read_b128 v[158:161], v144 offset:2048
	ds_read_b128 v[162:165], v144 offset:3072
	ds_read_b128 v[166:169], v145
	ds_read_b128 v[170:173], v145 offset:1024
	ds_read_b128 v[174:177], v145 offset:2048
	ds_read_b128 v[180:183], v145 offset:3072
	s_add_u32 s10, s44, 0x4000
	s_addc_u32 s11, s45, 0
	s_mov_b32 m0, s46
	v_lshl_add_u64 v[216:217], s[10:11], 0, v[130:131]
	ds_read_b128 v[184:187], v156 offset:32768
	ds_read_b128 v[188:191], v156 offset:33792
	ds_read_b128 v[192:195], v156 offset:34816
	ds_read_b128 v[196:199], v156 offset:35840
	ds_read_b128 v[200:203], v156 offset:36864
	ds_read_b128 v[204:207], v156 offset:37888
	ds_read_b128 v[208:211], v156 offset:38912
	ds_read_b128 v[212:215], v156 offset:39936
	global_load_lds_dwordx4 v[216:217], off
	v_lshl_add_u64 v[216:217], s[10:11], 0, v[134:135]
	s_mov_b32 m0, s47
	s_nop 0
	global_load_lds_dwordx4 v[216:217], off
	s_sleep 2
	s_waitcnt vmcnt(8)
	s_waitcnt lgkmcnt(0)
	s_barrier
	s_setprio 1
	s_waitcnt lgkmcnt(0)
	v_mfma_f32_16x16x32_bf16 v[122:125], v[146:149], v[184:187], v[122:125]
	v_mfma_f32_16x16x32_bf16 v[114:117], v[158:161], v[184:187], v[114:117]
	v_mfma_f32_16x16x32_bf16 v[98:101], v[158:161], v[192:195], v[98:101]
	v_mfma_f32_16x16x32_bf16 v[106:109], v[146:149], v[192:195], v[106:109]
	v_mfma_f32_16x16x32_bf16 v[88:91], v[146:149], v[200:203], v[88:91]
	v_mfma_f32_16x16x32_bf16 v[80:83], v[158:161], v[200:203], v[80:83]
	v_mfma_f32_16x16x32_bf16 v[60:63], v[158:161], v[208:211], v[60:63]
	v_mfma_f32_16x16x32_bf16 v[72:75], v[146:149], v[208:211], v[72:75]
	v_mfma_f32_16x16x32_bf16 v[122:125], v[150:153], v[188:191], v[122:125]
	v_mfma_f32_16x16x32_bf16 v[114:117], v[162:165], v[188:191], v[114:117]
	v_mfma_f32_16x16x32_bf16 v[98:101], v[162:165], v[196:199], v[98:101]
	v_mfma_f32_16x16x32_bf16 v[106:109], v[150:153], v[196:199], v[106:109]
	v_mfma_f32_16x16x32_bf16 v[88:91], v[150:153], v[204:207], v[88:91]
	v_mfma_f32_16x16x32_bf16 v[80:83], v[162:165], v[204:207], v[80:83]
	v_mfma_f32_16x16x32_bf16 v[60:63], v[162:165], v[212:215], v[60:63]
	v_mfma_f32_16x16x32_bf16 v[72:75], v[150:153], v[212:215], v[72:75]
	s_setprio 0
	s_setprio 1
	v_mfma_f32_16x16x32_bf16 v[126:129], v[166:169], v[184:187], v[126:129]
	v_mfma_f32_16x16x32_bf16 v[118:121], v[174:177], v[184:187], v[118:121]
	v_mfma_f32_16x16x32_bf16 v[102:105], v[174:177], v[192:195], v[102:105]
	v_mfma_f32_16x16x32_bf16 v[110:113], v[166:169], v[192:195], v[110:113]
	v_mfma_f32_16x16x32_bf16 v[92:95], v[166:169], v[200:203], v[92:95]
	v_mfma_f32_16x16x32_bf16 v[84:87], v[174:177], v[200:203], v[84:87]
	v_mfma_f32_16x16x32_bf16 v[68:71], v[174:177], v[208:211], v[68:71]
	v_mfma_f32_16x16x32_bf16 v[76:79], v[166:169], v[208:211], v[76:79]
	v_mfma_f32_16x16x32_bf16 v[126:129], v[170:173], v[188:191], v[126:129]
	v_mfma_f32_16x16x32_bf16 v[118:121], v[180:183], v[188:191], v[118:121]
	v_mfma_f32_16x16x32_bf16 v[102:105], v[180:183], v[196:199], v[102:105]
	v_mfma_f32_16x16x32_bf16 v[110:113], v[170:173], v[196:199], v[110:113]
	v_mfma_f32_16x16x32_bf16 v[92:95], v[170:173], v[204:207], v[92:95]
	v_mfma_f32_16x16x32_bf16 v[84:87], v[180:183], v[204:207], v[84:87]
	v_mfma_f32_16x16x32_bf16 v[68:71], v[180:183], v[212:215], v[68:71]
	v_mfma_f32_16x16x32_bf16 v[76:79], v[170:173], v[212:215], v[76:79]
	s_setprio 0
	s_barrier
; #define PG8_BAR __builtin_amdgcn_s_barrier()
; template <class Epi, class Sched, bool ALIGN_EPI = false, bool SP2 = false>
; __device__ __forceinline__ void gemm_phase(PG8_LAS unsigned char* lds, const Gemm g, const Sched& S, const Epi& E) {
;     ...
;         if constexpr (Epi::PEEL) {
;             const char* a1 = cA + kstepA; const char* a2 = cA + 2 * kstepA; const char* b2 = cB + 2 * kstepB; const char* a3 = a2 + kstepA; const char* b3 = b2 + kstepB;
;             PG8_ITER(8);
;         }
;         for (int t = (Epi::PEEL ? 2 : 0); t < nt; t += 2) {
;             const bool last = (t == nt - 2);
;             const char* a1 = cA + (size_t)(t + 1) * kstepA;
;             const char* a2 = last ? nA : cA + (size_t)(t + 2) * kstepA; const char* b2 = last ? nB : cB + (size_t)(t + 2) * kstepB;
;             const char* a3 = a2 + kstepA; const char* b3 = b2 + kstepB;
;             PG8_ITER(8);
;         }
;     ...
;         if constexpr (ALIGN_EPI) { if (wr == 0) PG8_BAR; }
	s_mov_b32 m0, s99
	v_lshl_add_u64 v[154:155], v[154:155], 0, s[36:37]
	s_add_u32 s10, s42, 0x40080
	ds_read_b128 v[184:187], v156 offset:49152
	ds_read_b128 v[188:191], v156 offset:50176
	ds_read_b128 v[192:195], v156 offset:51200
	ds_read_b128 v[196:199], v156 offset:52224
	ds_read_b128 v[200:203], v156 offset:53248
	ds_read_b128 v[204:207], v156 offset:54272
	ds_read_b128 v[208:211], v156 offset:55296
	ds_read_b128 v[212:215], v156 offset:56320
	global_load_lds_dwordx4 v[154:155], off
	v_lshl_add_u64 v[154:155], v[178:179], 0, s[36:37]
	s_mov_b32 m0, vcc_lo
	s_addc_u32 s11, s43, 0
	global_load_lds_dwordx4 v[154:155], off
	v_lshl_add_u64 v[154:155], s[10:11], 0, v[132:133]
	s_mov_b32 m0, vcc_hi
	s_nop 0
	global_load_lds_dwordx4 v[154:155], off
	v_lshl_add_u64 v[154:155], s[10:11], 0, v[136:137]
	s_mov_b32 m0, s38
	s_nop 0
	global_load_lds_dwordx4 v[154:155], off
	v_lshl_add_u64 v[154:155], s[34:35], 0, v[130:131]
	s_mov_b32 m0, s49
	s_nop 0
	global_load_lds_dwordx4 v[154:155], off
	v_lshl_add_u64 v[154:155], s[34:35], 0, v[134:135]
	s_mov_b32 m0, s50
	s_nop 0
	global_load_lds_dwordx4 v[154:155], off
	s_sleep 2
	s_waitcnt vmcnt(8)
	s_waitcnt lgkmcnt(0)
	s_barrier
	s_setprio 1
	s_waitcnt lgkmcnt(0)
	v_mfma_f32_16x16x32_bf16 v[56:59], v[146:149], v[184:187], v[56:59]
	v_mfma_f32_16x16x32_bf16 v[48:51], v[158:161], v[184:187], v[48:51]
	v_mfma_f32_16x16x32_bf16 v[32:35], v[158:161], v[192:195], v[32:35]
	v_mfma_f32_16x16x32_bf16 v[40:43], v[146:149], v[192:195], v[40:43]
	v_mfma_f32_16x16x32_bf16 v[24:27], v[146:149], v[200:203], v[24:27]
	v_mfma_f32_16x16x32_bf16 v[16:19], v[158:161], v[200:203], v[16:19]
	v_mfma_f32_16x16x32_bf16 v[0:3], v[158:161], v[208:211], v[0:3]
	v_mfma_f32_16x16x32_bf16 v[8:11], v[146:149], v[208:211], v[8:11]
	v_mfma_f32_16x16x32_bf16 v[56:59], v[150:153], v[188:191], v[56:59]
	v_mfma_f32_16x16x32_bf16 v[48:51], v[162:165], v[188:191], v[48:51]
	v_mfma_f32_16x16x32_bf16 v[32:35], v[162:165], v[196:199], v[32:35]
	v_mfma_f32_16x16x32_bf16 v[40:43], v[150:153], v[196:199], v[40:43]
	v_mfma_f32_16x16x32_bf16 v[24:27], v[150:153], v[204:207], v[24:27]
	v_mfma_f32_16x16x32_bf16 v[16:19], v[162:165], v[204:207], v[16:19]
	v_mfma_f32_16x16x32_bf16 v[0:3], v[162:165], v[212:215], v[0:3]
	v_mfma_f32_16x16x32_bf16 v[8:11], v[150:153], v[212:215], v[8:11]
	s_setprio 0
	s_setprio 1
	v_mfma_f32_16x16x32_bf16 v[64:67], v[166:169], v[184:187], v[64:67]
	v_mfma_f32_16x16x32_bf16 v[52:55], v[174:177], v[184:187], v[52:55]
	v_mfma_f32_16x16x32_bf16 v[36:39], v[174:177], v[192:195], v[36:39]
	v_mfma_f32_16x16x32_bf16 v[44:47], v[166:169], v[192:195], v[44:47]
	v_mfma_f32_16x16x32_bf16 v[28:31], v[166:169], v[200:203], v[28:31]
	v_mfma_f32_16x16x32_bf16 v[20:23], v[174:177], v[200:203], v[20:23]
	v_mfma_f32_16x16x32_bf16 v[4:7], v[174:177], v[208:211], v[4:7]
	v_mfma_f32_16x16x32_bf16 v[12:15], v[166:169], v[208:211], v[12:15]
	v_mfma_f32_16x16x32_bf16 v[64:67], v[170:173], v[188:191], v[64:67]
	v_mfma_f32_16x16x32_bf16 v[52:55], v[180:183], v[188:191], v[52:55]
	v_mfma_f32_16x16x32_bf16 v[36:39], v[180:183], v[196:199], v[36:39]
	v_mfma_f32_16x16x32_bf16 v[44:47], v[170:173], v[196:199], v[44:47]
	v_mfma_f32_16x16x32_bf16 v[28:31], v[170:173], v[204:207], v[28:31]
	v_mfma_f32_16x16x32_bf16 v[20:23], v[180:183], v[204:207], v[20:23]
	v_mfma_f32_16x16x32_bf16 v[4:7], v[180:183], v[212:215], v[4:7]
	v_mfma_f32_16x16x32_bf16 v[12:15], v[170:173], v[212:215], v[12:15]
	s_setprio 0
	s_barrier
	s_add_i32 s18, s18, 2
	s_add_u32 s3, s3, 0x100
	s_addc_u32 s2, s2, 0
	s_add_u32 s0, s0, 0x800000
	s_addc_u32 s1, s1, 0
	s_cmp_gt_u32 s18, 13
	s_cbranch_scc0 .LBB0_478
	s_and_b64 vcc, exec, s[16:17]
	s_cbranch_vccz .LBB0_481
	s_barrier
